# k20 + attention: first K/Q LDS reads issued right after the LDS-fill barrier, ahead of the next item's prefetch address computation (wait/issue placement, sec 7.2/7.10)
# speedup vs baseline: 1.0074x; 1.0074x over previous
; __device__ void phase_attn(const Params& p, unsigned char* smem, int wave) {
;     ...
;     if ((int)blockIdx.x < npairs) { ATT_DECODE(blockIdx.x) ATT_LOAD(); }
;     for (int pr = blockIdx.x; pr < npairs; pr += gridDim.x) {
;         ATT_DECODE(pr)
;         bf16_t* ato = (bf16_t*)(p.ws + (br < 2 ? WS_RA + br * ATO_STRIDE_01 : WS_ATO2));
;         __syncthreads();
;         const int hs = fresh_tid(wave);
; #pragma unroll
;         for (int c_ = 0; c_ < 2; ++c_) { const int e = hs + 512 * c_; *(u32x4*)(Qs + (e >> 3) * ATT_LD + (e & 7) * 8) = qr[c_]; }
; #pragma unroll
;         for (int c_ = 0; c_ < 4; ++c_) { const int e = hs + 512 * c_; *(u32x4*)(Ks + (e >> 3) * ATT_LD + (e & 7) * 8) = kr[c_]; *(u32x4*)(Vs + (e >> 3) * ATT_LD + (e & 7) * 8) = vr[c_]; }
;         __syncthreads();
;         if (pr + (int)gridDim.x < npairs) { ATT_DECODE(pr + gridDim.x) ATT_LOAD(); }
;         const bf16x8 qf0 = *(const bf16x8*)(Qs + (16 * w4 + ql) * ATT_LD + gq * 8), qf1 = *(const bf16x8*)(Qs + (16 * w4 + ql) * ATT_LD + 32 + gq * 8);
.LBB0_722:
	s_waitcnt lgkmcnt(0)
	s_barrier
	v_mbcnt_lo_u32_b32 v12, -1, 0
	v_mbcnt_hi_u32_b32 v12, -1, v12
	s_add_i32 s56, s23, s93
	v_or_b32_e32 v13, s70, v12
	v_lshlrev_b32_e32 v12, 4, v12
	v_and_b32_e32 v12, 0x70, v12
	v_add_u32_e32 v12, 0, v12
	v_lshrrev_b32_e32 v14, 3, v13
	v_mad_u64_u32 v[46:47], s[18:19], v14, s33, v[12:13]
	v_add_u32_e32 v14, 0x200, v13
	v_lshrrev_b32_e32 v14, 3, v14
	v_mad_u64_u32 v[48:49], s[18:19], v14, s33, v[12:13]
	v_add_u32_e32 v14, 0x400, v13
	v_lshrrev_b32_e32 v14, 3, v14
	s_waitcnt vmcnt(18)
	ds_write_b128 v46, v[0:3]
	s_waitcnt vmcnt(17)
	ds_write_b128 v48, v[4:7]
	ds_write_b128 v46, v[16:19] offset:18432
	ds_write_b128 v46, v[20:23] offset:55296
	ds_write_b128 v48, v[8:11] offset:18432
	ds_write_b128 v48, v[24:27] offset:55296
	v_mad_u64_u32 v[46:47], s[18:19], v14, s33, v[12:13]
	v_add_u32_e32 v13, 0x600, v13
	s_cmpk_gt_i32 s56, 0x3bff
	v_lshrrev_b32_e32 v13, 3, v13
	s_cselect_b64 s[46:47], -1, 0
	v_mad_u64_u32 v[12:13], s[18:19], v13, s33, v[12:13]
	s_and_b64 vcc, exec, s[46:47]
	ds_write_b128 v46, v[28:31] offset:18432
	ds_write_b128 v46, v[32:35] offset:55296
	ds_write_b128 v12, v[36:39] offset:18432
	ds_write_b128 v12, v[40:43] offset:55296
	s_waitcnt lgkmcnt(0)
	s_barrier
	ds_read_b128 v[232:235], v140 offset:18432
	ds_read_b128 v[186:189], v140
	ds_read_b128 v[50:53], v140 offset:18496
	ds_read_b128 v[190:193], v140 offset:64
	ds_read_b128 v[54:57], v140 offset:20736
	ds_read_b128 v[58:61], v140 offset:20800
	s_cbranch_vccnz .LBB0_732
	s_mul_hi_i32 s18, s56, 0x66666667
	s_lshr_b32 s19, s18, 31
	s_ashr_i32 s18, s18, 8
	s_add_i32 s18, s18, s19
	s_mul_i32 s19, s18, 0xfffffd80
	s_mul_i32 s27, s18, 0xfffec000
	s_add_i32 s28, s49, s48
	s_add_i32 s19, s56, s19
	s_add_i32 s28, s28, s27
	s_and_b32 s26, s18, -8
	s_and_b32 s27, s28, 0xfffff800
	s_and_b32 s28, s19, 15
	s_add_i32 s29, s19, 0xfffffe00
	s_cmp_eq_u32 s26, 8
	s_cselect_b32 s26, 2, 4
	s_cselect_b32 s30, 3, 15
	s_cmp_lt_u32 s18, 8
	s_cselect_b32 s26, 0, s26
	s_cselect_b32 s30, 0, s30
	s_cmpk_lt_i32 s19, 0x200
	s_cselect_b32 s19, s28, s29
	s_cselect_b32 s27, s27, 0x10000
	s_cselect_b32 s28, s50, 0x4000
	s_and_b32 s29, s30, s19
	s_lshr_b32 s19, s19, s26
	v_mbcnt_lo_u32_b32 v0, -1, 0
	v_mbcnt_hi_u32_b32 v0, -1, v0
	s_lshl_b32 s18, s18, 6
	v_or_b32_e32 v13, s70, v0
	s_lshl_b32 s19, s19, 7
	s_and_b32 s18, s18, 0x1c0
	v_lshlrev_b32_e32 v0, 3, v0
	v_ashrrev_i32_e32 v8, 3, v13
	v_add_u32_e32 v2, 0x200, v13
	v_and_or_b32 v12, v0, 56, s18
	v_add_u32_e32 v0, s19, v8
	v_ashrrev_i32_e32 v24, 3, v2
	s_or_b32 s27, s29, s27
	v_lshlrev_b32_e32 v0, s26, v0
	v_add_u32_e32 v2, s19, v24
	v_add_u32_e32 v0, s27, v0
	v_lshlrev_b32_e32 v2, s26, v2
	v_mul_lo_u32 v0, v0, s3
	v_add_u32_e32 v2, s27, v2
	v_or_b32_e32 v14, v0, v12
	v_mul_lo_u32 v2, v2, s3
	v_lshl_add_u64 v[0:1], v[14:15], 1, s[38:39]
	v_or_b32_e32 v14, v2, v12
	v_lshl_add_u64 v[4:5], v[14:15], 1, s[38:39]
	global_load_dwordx4 v[0:3], v[0:1], off
	s_nop 0
	global_load_dwordx4 v[4:7], v[4:5], off
	s_sub_i32 s29, s19, 64
	s_lshr_b32 s28, s28, s26
	v_add_u32_e32 v14, s29, v8
	v_mov_b32_e32 v10, v44
	v_mov_b32_e32 v11, v44
	v_cmp_lt_i32_e32 vcc, -1, v14
	v_cmp_gt_i32_e64 s[18:19], s28, v14
	v_mov_b32_e32 v8, 0
	v_mov_b32_e32 v9, v44
	v_mov_b64_e32 v[18:19], v[10:11]
	v_mov_b64_e32 v[22:23], v[10:11]
	s_and_b64 s[30:31], vcc, s[18:19]
	v_mov_b64_e32 v[16:17], v[8:9]
	v_mov_b64_e32 v[20:21], v[8:9]
	s_and_saveexec_b64 s[18:19], s[30:31]
	s_cbranch_execz .LBB0_725
	v_lshlrev_b32_e32 v14, s26, v14
	v_add_u32_e32 v14, s27, v14
	v_mul_lo_u32 v14, v14, s3
	v_or_b32_e32 v14, v14, v12
	v_lshl_add_u64 v[20:21], v[14:15], 1, s[38:39]
	global_load_dwordx4 v[16:19], v[20:21], off offset:1024
	s_nop 0
	global_load_dwordx4 v[20:23], v[20:21], off offset:2048

; __device__ void phase_attn(const Params& p, unsigned char* smem, int wave) {
;     ...
;         const bf16x8 qf0 = *(const bf16x8*)(Qs + (16 * w4 + ql) * ATT_LD + gq * 8), qf1 = *(const bf16x8*)(Qs + (16 * w4 + ql) * ATT_LD + 32 + gq * 8);
;         f32x4 sc[10];
; #pragma unroll
;         for (int kt = 0; kt < 9; ++kt) { const bf16_t* kr = Ks + (16 * w4 + 16 * kt + ql) * ATT_LD + gq * 8;
;             f32x4 a = (f32x4){0.f, 0.f, 0.f, 0.f};
;             a = __builtin_amdgcn_mfma_f32_16x16x32_bf16(*(const bf16x8*)kr, qf0, a, 0, 0, 0);
;             a = __builtin_amdgcn_mfma_f32_16x16x32_bf16(*(const bf16x8*)(kr + 32), qf1, a, 0, 0, 0);
;             sc[kt] = a; if (kt % 3 == 2) __builtin_amdgcn_sched_barrier(0); }
;         const float slope = exp2f(-(float)(h + 1)) * (float)d * 1.4426950408889634f;
;         const int qi = i0 + 16 * w4 + ql;
;         float mx = -1e30f;
; #pragma unroll
;         for (int kt = 0; kt < 9; ++kt)
; #pragma unroll
;             for (int j = 0; j < 4; ++j) { const int rel = 16 * kt + 4 * gq + j - 64 - ql; const int jk = qi + rel;
;                 const bool relok = (kt == 0) ? (rel >= -64) : ((kt == 8) ? (rel <= 64) : true);
;                 const bool ok = relok && ((unsigned)jk < (unsigned)Ls);
;                 const float v = ok ? sc[kt][j] * 0.18033688011112042f - slope * fabsf((float)rel) : -1e30f;
;                 sc[kt][j] = v; mx = fmaxf(mx, v); }
.LBB0_732:
	v_readlane_b32 s28, v253, 8
	v_readlane_b32 s30, v253, 10
	v_readlane_b32 s31, v253, 11
	s_add_u32 s59, s30, s20
	s_mul_i32 s18, s22, 0xfffffd80
	s_waitcnt lgkmcnt(4)
	v_mfma_f32_16x16x32_bf16 v[46:49], v[232:235], v[186:189], 0
	s_mul_i32 s19, s22, 0xfffec000
	s_addc_u32 s60, s31, s21
	s_add_i32 s18, s23, s18
	s_waitcnt lgkmcnt(2)
	v_mfma_f32_16x16x32_bf16 v[194:197], v[50:53], v[190:193], v[46:49]
	s_add_i32 s19, s48, s19
	s_and_b32 s57, s22, 7
	s_and_b32 s19, s19, 0xfffff800
	ds_read_b128 v[46:49], v140 offset:23040
	s_waitcnt lgkmcnt(2)
	v_mfma_f32_16x16x32_bf16 v[50:53], v[54:57], v[186:189], 0
	ds_read_b128 v[54:57], v140 offset:23104
	s_and_b32 s20, s18, 15
	s_add_i32 s21, s18, 0xfffffe00
	s_cmpk_lt_i32 s18, 0x200
	s_cselect_b32 s18, s20, s21
	s_cselect_b32 s20, s50, 0x4000
	s_cselect_b32 s61, s19, 0x10000
	s_cmp_eq_u32 s42, 1
	s_cselect_b32 s19, 4, 16
	s_cselect_b32 s21, 2, 4
	s_cmp_lt_u32 s22, 8
	s_waitcnt lgkmcnt(1)
	v_mfma_f32_16x16x32_bf16 v[46:49], v[46:49], v[186:189], 0
	s_cselect_b32 s22, 1, s19
	s_cselect_b32 s58, 0, s21
	s_add_i32 s19, s22, -1
	s_lshr_b32 s63, s20, s58
	s_and_b32 s62, s19, s18
	s_lshr_b32 s20, s18, s58
	v_readlane_b32 s29, v253, 9
	v_mfma_f32_16x16x32_bf16 v[198:201], v[58:61], v[190:193], v[50:53]
	s_waitcnt lgkmcnt(0)
	v_mfma_f32_16x16x32_bf16 v[202:205], v[54:57], v[190:193], v[46:49]
	s_nop 2
	ds_read_b128 v[46:49], v140 offset:25344
	ds_read_b128 v[50:53], v140 offset:25408
	ds_read_b128 v[54:57], v140 offset:27648
	ds_read_b128 v[58:61], v140 offset:27712
	s_waitcnt lgkmcnt(3)
	v_mfma_f32_16x16x32_bf16 v[46:49], v[46:49], v[186:189], 0
	s_waitcnt lgkmcnt(2)
	v_mfma_f32_16x16x32_bf16 v[206:209], v[50:53], v[190:193], v[46:49]
	ds_read_b128 v[50:53], v140 offset:30016
	s_nop 4
	ds_read_b128 v[46:49], v140 offset:29952
	s_waitcnt lgkmcnt(3)
	v_mfma_f32_16x16x32_bf16 v[54:57], v[54:57], v[186:189], 0
	s_waitcnt lgkmcnt(0)
	v_mfma_f32_16x16x32_bf16 v[46:49], v[46:49], v[186:189], 0
	v_mfma_f32_16x16x32_bf16 v[62:65], v[58:61], v[190:193], v[54:57]
	v_mfma_f32_16x16x32_bf16 v[58:61], v[50:53], v[190:193], v[46:49]
	s_nop 5
	ds_read_b128 v[46:49], v140 offset:32256
	ds_read_b128 v[50:53], v140 offset:32320
	ds_read_b128 v[54:57], v140 offset:34560
	ds_read_b128 v[210:213], v140 offset:34624
	s_waitcnt lgkmcnt(3)
	v_mfma_f32_16x16x32_bf16 v[46:49], v[46:49], v[186:189], 0
	s_waitcnt lgkmcnt(1)
	v_mfma_f32_16x16x32_bf16 v[214:217], v[54:57], v[186:189], 0
	v_mfma_f32_16x16x32_bf16 v[54:57], v[50:53], v[190:193], v[46:49]
	s_nop 4
	ds_read_b128 v[46:49], v140 offset:36864
	s_waitcnt lgkmcnt(1)
	v_mfma_f32_16x16x32_bf16 v[50:53], v[210:213], v[190:193], v[214:217]
	ds_read_b128 v[210:213], v140 offset:36928
	s_waitcnt lgkmcnt(1)
	v_mfma_f32_16x16x32_bf16 v[46:49], v[46:49], v[186:189], 0
	s_waitcnt lgkmcnt(0)
	v_mfma_f32_16x16x32_bf16 v[46:49], v[210:213], v[190:193], v[46:49]
	s_add_i32 s18, s57, 1
	v_cvt_f32_ubyte0_e32 v12, s18
	v_cmp_lt_f32_e32 vcc, s51, v12
	s_and_b64 s[18:19], vcc, exec
	s_cselect_b32 s18, 0xffffffc0, 0
	v_cndmask_b32_e32 v13, 0, v181, vcc
	v_sub_f32_e32 v12, v13, v12
	v_exp_f32_e32 v12, v12
	v_lshl_add_u32 v139, s20, 7, v67
	v_cvt_f32_ubyte0_e32 v13, s22
	v_or_b32_e32 v45, v139, v66
	v_ldexp_f32 v12, v12, s18
	v_mul_f32_e32 v13, v12, v13
	v_add_u32_e32 v12, v45, v143
	v_cmp_gt_u32_e64 s[26:27], s63, v12
	v_add_u32_e32 v12, v45, v144
	v_cmp_gt_u32_e64 s[28:29], s63, v12
	v_add_u32_e32 v12, v45, v145
	v_cmp_gt_u32_e64 s[30:31], s63, v12
	v_add_u32_e32 v12, v45, v146
	v_cmp_gt_u32_e64 s[34:35], s63, v12
	v_add_u32_e32 v12, v45, v174
	v_cmp_gt_u32_e64 s[22:23], s63, v12
	v_add_u32_e32 v12, v45, v175
	v_cmp_gt_u32_e64 s[20:21], s63, v12
	v_add_u32_e32 v12, v45, v176
	v_cmp_gt_u32_e32 vcc, s63, v12
	v_add_u32_e32 v12, v45, v177
	v_cmp_gt_u32_e64 s[18:19], s63, v12
	v_mov_b32_e32 v12, v49
	v_pk_mul_f32 v[12:13], v[12:13], s[44:45]
	v_mov_b32_e32 v186, v194
	v_mov_b32_e32 v187, v13
	v_pk_mul_f32 v[186:187], v[68:69], v[186:187]
	s_and_b64 s[26:27], s[24:25], s[26:27]
	v_sub_f32_e32 v49, v186, v187
	v_mov_b32_e32 v186, v195
	v_mov_b32_e32 v187, v13
	v_pk_mul_f32 v[186:187], v[70:71], v[186:187]
	v_cndmask_b32_e64 v194, v182, v49, s[26:27]
	v_sub_f32_e32 v49, v186, v187
	v_mov_b32_e32 v186, v196
	v_mov_b32_e32 v187, v13
	s_and_b64 s[26:27], s[4:5], s[28:29]
	v_pk_mul_f32 v[186:187], v[72:73], v[186:187]
	v_cndmask_b32_e64 v195, v182, v49, s[26:27]
	v_sub_f32_e32 v186, v186, v187
	s_and_b64 s[26:27], s[6:7], s[30:31]
	v_cndmask_b32_e64 v196, v182, v186, s[26:27]
	v_mov_b32_e32 v186, v197
	v_mov_b32_e32 v187, v13
	v_pk_mul_f32 v[186:187], v[74:75], v[186:187]
	s_and_b64 s[26:27], s[8:9], s[34:35]
	v_sub_f32_e32 v186, v186, v187
	v_cndmask_b32_e64 v197, v182, v186, s[26:27]
	v_mov_b32_e32 v186, v198
	v_mov_b32_e32 v187, v13
	v_add_u32_e32 v14, v45, v147
	v_pk_mul_f32 v[186:187], v[76:77], v[186:187]
	v_cmp_gt_u32_e64 s[26:27], s63, v14
	v_sub_f32_e32 v186, v186, v187
	v_mov_b32_e32 v187, v13
	v_cndmask_b32_e64 v14, v182, v186, s[26:27]
	v_mov_b32_e32 v186, v199
	v_add_u32_e32 v188, v45, v148
	v_pk_mul_f32 v[186:187], v[78:79], v[186:187]
	v_cmp_gt_u32_e64 s[26:27], s63, v188
	v_sub_f32_e32 v186, v186, v187
	v_mov_b32_e32 v187, v13
	v_cndmask_b32_e64 v188, v182, v186, s[26:27]
	v_mov_b32_e32 v186, v200
	v_add_u32_e32 v189, v45, v149
	v_pk_mul_f32 v[186:187], v[80:81], v[186:187]
	v_cmp_gt_u32_e64 s[26:27], s63, v189
	v_sub_f32_e32 v186, v186, v187
	v_mov_b32_e32 v187, v13
	v_cndmask_b32_e64 v189, v182, v186, s[26:27]
	v_mov_b32_e32 v186, v201
	v_add_u32_e32 v190, v45, v150
	v_pk_mul_f32 v[186:187], v[82:83], v[186:187]
	v_cmp_gt_u32_e64 s[26:27], s63, v190
	v_sub_f32_e32 v186, v186, v187
; __device__ void phase_attn(const Params& p, unsigned char* smem, int wave) {
;     ...
; #pragma unroll
;         for (int kt = 0; kt < 9; ++kt)
; #pragma unroll
;             for (int j = 0; j < 4; ++j) { const int rel = 16 * kt + 4 * gq + j - 64 - ql; const int jk = qi + rel;
;                 const bool relok = (kt == 0) ? (rel >= -64) : ((kt == 8) ? (rel <= 64) : true);
;                 const bool ok = relok && ((unsigned)jk < (unsigned)Ls);
;                 const float v = ok ? sc[kt][j] * 0.18033688011112042f - slope * fabsf((float)rel) : -1e30f;
;                 sc[kt][j] = v; mx = fmaxf(mx, v); }
	v_mov_b32_e32 v187, v13
	v_cndmask_b32_e64 v190, v182, v186, s[26:27]
	v_mov_b32_e32 v186, v202
	v_add_u32_e32 v191, v45, v151
	v_pk_mul_f32 v[186:187], v[84:85], v[186:187]
	v_cmp_gt_u32_e64 s[26:27], s63, v191
	v_sub_f32_e32 v186, v186, v187
	v_mov_b32_e32 v187, v13
	v_cndmask_b32_e64 v191, v182, v186, s[26:27]
	v_mov_b32_e32 v186, v203
	v_add_u32_e32 v192, v45, v152
	v_pk_mul_f32 v[186:187], v[86:87], v[186:187]
	v_cmp_gt_u32_e64 s[26:27], s63, v192
	v_sub_f32_e32 v186, v186, v187
	v_mov_b32_e32 v187, v13
	v_cndmask_b32_e64 v192, v182, v186, s[26:27]
	v_mov_b32_e32 v186, v204
	v_add_u32_e32 v193, v45, v153
	v_pk_mul_f32 v[186:187], v[88:89], v[186:187]
	v_cmp_gt_u32_e64 s[26:27], s63, v193
	v_sub_f32_e32 v186, v186, v187
	v_mov_b32_e32 v187, v13
	v_cndmask_b32_e64 v193, v182, v186, s[26:27]
	v_mov_b32_e32 v186, v205
	v_add_u32_e32 v210, v45, v154
	v_pk_mul_f32 v[186:187], v[90:91], v[186:187]
	v_cmp_gt_u32_e64 s[26:27], s63, v210
	v_sub_f32_e32 v186, v186, v187
	v_mov_b32_e32 v187, v13
	v_cndmask_b32_e64 v198, v182, v186, s[26:27]
	v_mov_b32_e32 v186, v206
	v_add_u32_e32 v211, v45, v155
	v_pk_mul_f32 v[186:187], v[92:93], v[186:187]
	v_cmp_gt_u32_e64 s[26:27], s63, v211
	v_sub_f32_e32 v186, v186, v187
	v_mov_b32_e32 v187, v13
	v_cndmask_b32_e64 v199, v182, v186, s[26:27]
	v_mov_b32_e32 v186, v207
	v_add_u32_e32 v212, v45, v156
	v_pk_mul_f32 v[186:187], v[94:95], v[186:187]
	v_cmp_gt_u32_e64 s[26:27], s63, v212
	v_sub_f32_e32 v186, v186, v187
	v_mov_b32_e32 v187, v13
	v_cndmask_b32_e64 v200, v182, v186, s[26:27]
	v_mov_b32_e32 v186, v208
	v_add_u32_e32 v213, v45, v157
	v_pk_mul_f32 v[186:187], v[96:97], v[186:187]
	v_cmp_gt_u32_e64 s[26:27], s63, v213
	v_sub_f32_e32 v186, v186, v187
	v_mov_b32_e32 v187, v13
	v_cndmask_b32_e64 v201, v182, v186, s[26:27]
	v_mov_b32_e32 v186, v209
	v_add_u32_e32 v214, v45, v158
	v_pk_mul_f32 v[186:187], v[98:99], v[186:187]
	v_cmp_gt_u32_e64 s[26:27], s63, v214
	v_sub_f32_e32 v186, v186, v187
	v_mov_b32_e32 v187, v13
	v_cndmask_b32_e64 v202, v182, v186, s[26:27]
	v_mov_b32_e32 v186, v62
	v_add_u32_e32 v215, v45, v142
	v_pk_mul_f32 v[186:187], v[100:101], v[186:187]
	v_cmp_gt_u32_e64 s[26:27], s63, v215
	v_sub_f32_e32 v62, v186, v187
	v_add_u32_e32 v216, v45, v159
	v_cndmask_b32_e64 v186, v182, v62, s[26:27]
	v_mov_b32_e32 v62, v63
	v_mov_b32_e32 v63, v13
	v_pk_mul_f32 v[62:63], v[102:103], v[62:63]
	v_cmp_gt_u32_e64 s[26:27], s63, v216
	v_sub_f32_e32 v62, v62, v63
	v_mov_b32_e32 v63, v13
	v_cndmask_b32_e64 v187, v182, v62, s[26:27]
	v_mov_b32_e32 v62, v64
	v_add_u32_e32 v217, v45, v160
	v_pk_mul_f32 v[62:63], v[104:105], v[62:63]
	v_cmp_gt_u32_e64 s[26:27], s63, v217
	v_sub_f32_e32 v62, v62, v63
	v_mov_b32_e32 v63, v13
	v_cndmask_b32_e64 v64, v182, v62, s[26:27]
	v_mov_b32_e32 v62, v65
	v_add_u32_e32 v218, v45, v161
	v_pk_mul_f32 v[62:63], v[106:107], v[62:63]
	v_cmp_gt_u32_e64 s[26:27], s63, v218
	v_sub_f32_e32 v62, v62, v63
	v_mov_b32_e32 v63, v13
	v_cndmask_b32_e64 v65, v182, v62, s[26:27]
	v_mov_b32_e32 v62, v58
	v_add_u32_e32 v219, v45, v162
	v_pk_mul_f32 v[62:63], v[62:63], v[108:109]
	v_cmp_gt_u32_e64 s[26:27], s63, v219
	v_sub_f32_e32 v58, v62, v63
	v_add_u32_e32 v220, v45, v163
	v_cndmask_b32_e64 v62, v182, v58, s[26:27]
	v_mov_b32_e32 v58, v59
	v_mov_b32_e32 v59, v13
	v_pk_mul_f32 v[58:59], v[58:59], v[110:111]
	v_cmp_gt_u32_e64 s[26:27], s63, v220
	v_sub_f32_e32 v58, v58, v59
	v_mov_b32_e32 v59, v13
	v_cndmask_b32_e64 v63, v182, v58, s[26:27]
	v_mov_b32_e32 v58, v60
	v_add_u32_e32 v221, v45, v164
	v_pk_mul_f32 v[58:59], v[58:59], v[112:113]
	v_cmp_gt_u32_e64 s[26:27], s63, v221
	v_sub_f32_e32 v58, v58, v59
	v_mov_b32_e32 v59, v13
	v_cndmask_b32_e64 v60, v182, v58, s[26:27]
	v_mov_b32_e32 v58, v61
	v_add_u32_e32 v222, v45, v165
	v_pk_mul_f32 v[58:59], v[58:59], v[114:115]
	v_cmp_gt_u32_e64 s[26:27], s63, v222
	v_sub_f32_e32 v58, v58, v59
	v_mov_b32_e32 v59, v13
	v_cndmask_b32_e64 v61, v182, v58, s[26:27]
	v_mov_b32_e32 v58, v54
	v_add_u32_e32 v223, v45, v166
	v_pk_mul_f32 v[58:59], v[58:59], v[116:117]
	v_cmp_gt_u32_e64 s[26:27], s63, v223
	v_sub_f32_e32 v54, v58, v59
	v_add_u32_e32 v224, v45, v167
	v_cndmask_b32_e64 v58, v182, v54, s[26:27]
	v_mov_b32_e32 v54, v55
	v_mov_b32_e32 v55, v13
	v_pk_mul_f32 v[54:55], v[54:55], v[118:119]
	v_cmp_gt_u32_e64 s[26:27], s63, v224
	v_sub_f32_e32 v54, v54, v55
	v_mov_b32_e32 v55, v13
	v_cndmask_b32_e64 v59, v182, v54, s[26:27]
	v_mov_b32_e32 v54, v56
	v_add_u32_e32 v225, v45, v168
	v_pk_mul_f32 v[54:55], v[54:55], v[120:121]
	v_cmp_gt_u32_e64 s[26:27], s63, v225
	v_sub_f32_e32 v54, v54, v55
	v_mov_b32_e32 v55, v13
	v_cndmask_b32_e64 v56, v182, v54, s[26:27]
	v_mov_b32_e32 v54, v57
	v_add_u32_e32 v226, v45, v169
	v_pk_mul_f32 v[54:55], v[54:55], v[122:123]
	v_cmp_gt_u32_e64 s[26:27], s63, v226
	v_sub_f32_e32 v54, v54, v55
	v_mov_b32_e32 v55, v13
	v_cndmask_b32_e64 v57, v182, v54, s[26:27]
	v_mov_b32_e32 v54, v50
	v_add_u32_e32 v227, v45, v170
	v_pk_mul_f32 v[54:55], v[54:55], v[124:125]
	v_cmp_gt_u32_e64 s[26:27], s63, v227
	v_sub_f32_e32 v50, v54, v55
	v_max3_f32 v49, v194, s52, v195
	v_cndmask_b32_e64 v54, v182, v50, s[26:27]
	v_mov_b32_e32 v50, v51
	v_mov_b32_e32 v51, v13
	v_add_u32_e32 v228, v45, v171
	v_max3_f32 v49, v49, v196, v197
	v_pk_mul_f32 v[50:51], v[50:51], v[126:127]
	v_max3_f32 v49, v49, v14, v188
	v_sub_f32_e32 v50, v50, v51
	v_cmp_gt_u32_e64 s[26:27], s63, v228
	v_max3_f32 v49, v49, v189, v190
	v_mov_b32_e32 v51, v13
	v_cndmask_b32_e64 v55, v182, v50, s[26:27]
	v_mov_b32_e32 v50, v52
	v_add_u32_e32 v229, v45, v172
	v_max3_f32 v49, v49, v191, v192
	v_pk_mul_f32 v[50:51], v[50:51], v[128:129]
	v_max3_f32 v49, v49, v193, v198
; __device__ __forceinline__ unsigned cvtpk(float lo, float hi) { const f32v2_t v = {lo, hi}; const bf16v2_t b = __builtin_convertvector(v, bf16v2_t); return __builtin_bit_cast(unsigned, b); }
; __device__ __forceinline__ v4i16_t lds_tr16(const bf16_t* p) { return __builtin_amdgcn_ds_read_tr16_b64_v4i16((LAS v4i16_t*)p); }
; __device__ void phase_attn(const Params& p, unsigned char* smem, int wave) {
;     ...
;         mx = fmaxf(mx, __shfl_xor(mx, 16)); mx = fmaxf(mx, __shfl_xor(mx, 32));
;         float den = 0.f;
; #pragma unroll
;         for (int kt = 0; kt < 9; ++kt)
; #pragma unroll
;             for (int j = 0; j < 4; ++j) { const float pv = __builtin_amdgcn_exp2f(sc[kt][j] - mx); sc[kt][j] = pv; den += pv; }
;         sc[9] = (f32x4){0.f, 0.f, 0.f, 0.f};
;         den += __shfl_xor(den, 16); den += __shfl_xor(den, 32);
;         f32x4 oacc[4];
; #pragma unroll
;         for (int et = 0; et < 4; ++et) oacc[et] = (f32x4){0.f, 0.f, 0.f, 0.f};
; #pragma unroll
;         for (int ks = 0; ks < 5; ++ks) {
;             u32x4 pu; pu.x = cvtpk(sc[2 * ks][0], sc[2 * ks][1]); pu.y = cvtpk(sc[2 * ks][2], sc[2 * ks][3]); pu.z = cvtpk(sc[2 * ks + 1][0], sc[2 * ks + 1][1]); pu.w = cvtpk(sc[2 * ks + 1][2], sc[2 * ks + 1][3]);
;             const bf16x8 pf = __builtin_bit_cast(bf16x8, pu);
;             const bf16_t* vrow = Vs + (16 * w4 + 32 * ks + 4 * gq + (ql >> 2)) * ATT_LD + 4 * (ql & 3);
; #pragma unroll
;             for (int et = 0; et < 4; ++et) {
;                 const v4i16_t t0 = lds_tr16(vrow + 16 * et);
;                 v4i16_t t1 = (v4i16_t){0, 0, 0, 0};
;                 if (ks < 4) t1 = lds_tr16(vrow + 16 * ATT_LD + 16 * et);
;                 const bf16x8 vf = __builtin_shufflevector(t0, t1, 0, 1, 2, 3, 4, 5, 6, 7);
;                 oacc[et] = __builtin_amdgcn_mfma_f32_16x16x32_bf16(pf, vf, oacc[et], 0, 0, 0); }
	v_sub_f32_e32 v50, v50, v51
	v_cmp_gt_u32_e64 s[26:27], s63, v229
	v_max3_f32 v49, v49, v199, v200
	v_mov_b32_e32 v51, v13
	v_cndmask_b32_e64 v52, v182, v50, s[26:27]
	v_mov_b32_e32 v50, v53
	v_add_u32_e32 v230, v45, v173
	v_max3_f32 v49, v49, v201, v202
	v_pk_mul_f32 v[50:51], v[50:51], v[130:131]
	v_max3_f32 v49, v49, v186, v187
	v_sub_f32_e32 v50, v50, v51
	v_cmp_gt_u32_e64 s[26:27], s63, v230
	v_max3_f32 v49, v49, v64, v65
	v_mov_b32_e32 v51, v13
	v_cndmask_b32_e64 v53, v182, v50, s[26:27]
	v_mov_b32_e32 v50, v46
	v_max3_f32 v49, v49, v62, v63
	v_pk_mul_f32 v[50:51], v[50:51], v[132:133]
	v_max3_f32 v49, v49, v60, v61
	v_sub_f32_e32 v46, v50, v51
	s_and_b64 s[22:23], s[10:11], s[22:23]
	v_max3_f32 v49, v49, v58, v59
	v_cndmask_b32_e64 v50, v182, v46, s[22:23]
	v_mov_b32_e32 v46, v47
	v_mov_b32_e32 v47, v13
	v_max3_f32 v49, v49, v56, v57
	v_pk_mul_f32 v[46:47], v[46:47], v[134:135]
	v_max3_f32 v49, v49, v54, v55
	v_sub_f32_e32 v46, v46, v47
	s_and_b64 s[20:21], s[12:13], s[20:21]
	v_max3_f32 v49, v49, v52, v53
	v_cndmask_b32_e64 v51, v182, v46, s[20:21]
	v_max3_f32 v203, v49, v50, v51
	v_mov_b32_e32 v49, v13
	v_pk_mul_f32 v[46:47], v[48:49], v[136:137]
	s_and_b64 vcc, s[14:15], vcc
	v_sub_f32_e32 v46, v46, v47
	v_and_b32_e32 v206, 64, v183
	v_cndmask_b32_e32 v47, v182, v46, vcc
	v_fma_f32 v12, -v13, v178, v12
	s_and_b64 vcc, s[16:17], s[18:19]
	v_xor_b32_e32 v46, 16, v183
	v_add_u32_e32 v48, 64, v206
	v_cndmask_b32_e32 v12, v182, v12, vcc
	v_cmp_lt_i32_e32 vcc, v46, v48
	v_max3_f32 v13, v203, v47, v12
	s_nop 0
	v_cndmask_b32_e32 v46, v183, v46, vcc
	v_lshlrev_b32_e32 v203, 2, v46
	ds_bpermute_b32 v46, v203, v13
	s_waitcnt lgkmcnt(0)
	v_max_f32_e32 v46, v46, v46
	v_max_f32_e32 v13, v13, v46
	v_xor_b32_e32 v46, 32, v183
	v_cmp_lt_i32_e32 vcc, v46, v48
	s_nop 1
	v_cndmask_b32_e32 v46, v183, v46, vcc
	v_lshlrev_b32_e32 v204, 2, v46
	ds_bpermute_b32 v46, v204, v13
	s_waitcnt lgkmcnt(0)
	v_max_f32_e32 v46, v46, v46
	v_max_f32_e32 v46, v13, v46
	v_sub_f32_e32 v13, v194, v46
	v_exp_f32_e32 v13, v13
	v_sub_f32_e32 v49, v195, v46
	v_exp_f32_e32 v49, v49
	v_sub_f32_e32 v194, v196, v46
	v_exp_f32_e32 v194, v194
	v_sub_f32_e32 v195, v197, v46
	v_exp_f32_e32 v195, v195
	v_sub_f32_e32 v14, v14, v46
	v_add_f32_e32 v48, 0, v13
	v_exp_f32_e32 v14, v14
	v_sub_f32_e32 v188, v188, v46
	v_add_f32_e32 v48, v49, v48
	v_exp_f32_e32 v188, v188
	v_sub_f32_e32 v189, v189, v46
	v_add_f32_e32 v48, v194, v48
	v_exp_f32_e32 v189, v189
	v_sub_f32_e32 v190, v190, v46
	v_add_f32_e32 v48, v195, v48
	v_exp_f32_e32 v190, v190
	v_sub_f32_e32 v191, v191, v46
	v_add_f32_e32 v48, v14, v48
	v_exp_f32_e32 v191, v191
	v_sub_f32_e32 v192, v192, v46
	v_add_f32_e32 v48, v188, v48
	v_exp_f32_e32 v192, v192
	v_sub_f32_e32 v193, v193, v46
	v_add_f32_e32 v48, v189, v48
	v_exp_f32_e32 v193, v193
	v_sub_f32_e32 v196, v198, v46
	v_add_f32_e32 v48, v190, v48
	v_exp_f32_e32 v196, v196
	v_sub_f32_e32 v197, v199, v46
	v_add_f32_e32 v48, v191, v48
	v_exp_f32_e32 v197, v197
	v_sub_f32_e32 v198, v200, v46
	v_add_f32_e32 v48, v192, v48
	v_exp_f32_e32 v198, v198
	v_sub_f32_e32 v199, v201, v46
	v_add_f32_e32 v48, v193, v48
	v_exp_f32_e32 v199, v199
	v_sub_f32_e32 v200, v202, v46
	v_add_f32_e32 v48, v196, v48
	v_exp_f32_e32 v200, v200
	v_sub_f32_e32 v186, v186, v46
	v_add_f32_e32 v48, v197, v48
	v_exp_f32_e32 v207, v186
	v_sub_f32_e32 v186, v187, v46
	v_add_f32_e32 v48, v198, v48
	v_exp_f32_e32 v208, v186
	v_sub_f32_e32 v64, v64, v46
	v_add_f32_e32 v48, v199, v48
	v_exp_f32_e32 v64, v64
	v_sub_f32_e32 v65, v65, v46
	v_add_f32_e32 v48, v200, v48
	v_exp_f32_e32 v65, v65
	v_sub_f32_e32 v62, v62, v46
	v_add_f32_e32 v48, v207, v48
	v_exp_f32_e32 v209, v62
	v_sub_f32_e32 v62, v63, v46
	v_add_f32_e32 v48, v208, v48
	v_exp_f32_e32 v210, v62
	v_sub_f32_e32 v60, v60, v46
	v_add_f32_e32 v48, v64, v48
	v_exp_f32_e32 v211, v60
	v_sub_f32_e32 v60, v61, v46
	v_add_f32_e32 v48, v65, v48
	v_exp_f32_e32 v212, v60
	v_sub_f32_e32 v58, v58, v46
	v_add_f32_e32 v48, v209, v48
	v_exp_f32_e32 v213, v58
	v_sub_f32_e32 v58, v59, v46
	v_add_f32_e32 v48, v210, v48
	v_exp_f32_e32 v214, v58
	v_sub_f32_e32 v56, v56, v46
	v_add_f32_e32 v48, v211, v48
	v_exp_f32_e32 v215, v56
	v_sub_f32_e32 v56, v57, v46
	v_add_f32_e32 v48, v212, v48
	v_exp_f32_e32 v216, v56
	v_sub_f32_e32 v54, v54, v46
	v_add_f32_e32 v48, v213, v48
	v_exp_f32_e32 v217, v54
	v_sub_f32_e32 v54, v55, v46
	v_add_f32_e32 v48, v214, v48
	v_exp_f32_e32 v218, v54
	v_sub_f32_e32 v52, v52, v46
	v_add_f32_e32 v48, v215, v48
	v_exp_f32_e32 v219, v52
	v_sub_f32_e32 v52, v53, v46
	v_add_f32_e32 v48, v216, v48
	v_exp_f32_e32 v220, v52
	v_sub_f32_e32 v50, v50, v46
	v_add_f32_e32 v48, v217, v48
	v_exp_f32_e32 v221, v50
	v_add_f32_e32 v48, v218, v48
	v_add_f32_e32 v48, v219, v48
	v_add_f32_e32 v48, v220, v48
	v_add_f32_e32 v201, v221, v48
	v_sub_f32_e32 v48, v51, v46
	v_exp_f32_e32 v222, v48
	v_sub_f32_e32 v47, v47, v46
	v_cvt_pk_bf16_f32 v48, v13, v49
	v_exp_f32_e32 v13, v47
	v_sub_f32_e32 v12, v12, v46
	v_cvt_pk_bf16_f32 v50, v14, v188
	v_exp_f32_e32 v14, v12
	v_add_f32_e32 v12, v222, v201
	v_add_f32_e32 v12, v13, v12
	v_cvt_pk_bf16_f32 v49, v194, v195
	v_add_f32_e32 v12, v14, v12
	ds_bpermute_b32 v47, v203, v12
	v_cvt_pk_bf16_f32 v51, v189, v190
	ds_read_b64_tr_b16 v[54:55], v179 offset:57600
	ds_read_b64_tr_b16 v[52:53], v179 offset:55296
	ds_read_b64_tr_b16 v[56:57], v179 offset:55328
	ds_read_b64_tr_b16 v[60:61], v179 offset:55360
	ds_read_b64_tr_b16 v[186:187], v179 offset:55392
	ds_read_b64_tr_b16 v[58:59], v179 offset:57632
	ds_read_b64_tr_b16 v[62:63], v179 offset:57664
	ds_read_b64_tr_b16 v[188:189], v179 offset:57696
	s_waitcnt lgkmcnt(6)
; __device__ __forceinline__ unsigned cvtpk(float lo, float hi) { const f32v2_t v = {lo, hi}; const bf16v2_t b = __builtin_convertvector(v, bf16v2_t); return __builtin_bit_cast(unsigned, b); }
; __device__ __forceinline__ v4i16_t lds_tr16(const bf16_t* p) { return __builtin_amdgcn_ds_read_tr16_b64_v4i16((LAS v4i16_t*)p); }
; __device__ void phase_attn(const Params& p, unsigned char* smem, int wave) {
;     ...
; #pragma unroll
;         for (int ks = 0; ks < 5; ++ks) {
;             u32x4 pu; pu.x = cvtpk(sc[2 * ks][0], sc[2 * ks][1]); pu.y = cvtpk(sc[2 * ks][2], sc[2 * ks][3]); pu.z = cvtpk(sc[2 * ks + 1][0], sc[2 * ks + 1][1]); pu.w = cvtpk(sc[2 * ks + 1][2], sc[2 * ks + 1][3]);
;             const bf16x8 pf = __builtin_bit_cast(bf16x8, pu);
;             const bf16_t* vrow = Vs + (16 * w4 + 32 * ks + 4 * gq + (ql >> 2)) * ATT_LD + 4 * (ql & 3);
; #pragma unroll
;             for (int et = 0; et < 4; ++et) {
;                 const v4i16_t t0 = lds_tr16(vrow + 16 * et);
;                 v4i16_t t1 = (v4i16_t){0, 0, 0, 0};
;                 if (ks < 4) t1 = lds_tr16(vrow + 16 * ATT_LD + 16 * et);
;                 const bf16x8 vf = __builtin_shufflevector(t0, t1, 0, 1, 2, 3, 4, 5, 6, 7);
;                 oacc[et] = __builtin_amdgcn_mfma_f32_16x16x32_bf16(pf, vf, oacc[et], 0, 0, 0); }
;             __builtin_amdgcn_sched_barrier(0);
;         }
	v_mfma_f32_16x16x32_bf16 v[52:55], v[48:51], v[52:55], 0
	v_add_f32_e32 v47, v12, v47
	ds_bpermute_b32 v223, v204, v47
	s_waitcnt lgkmcnt(3)
	v_mfma_f32_16x16x32_bf16 v[56:59], v[48:51], v[56:59], 0
	s_waitcnt lgkmcnt(2)
	v_mfma_f32_16x16x32_bf16 v[60:63], v[48:51], v[60:63], 0
	s_waitcnt lgkmcnt(1)
	v_mfma_f32_16x16x32_bf16 v[48:51], v[48:51], v[186:189], 0
	v_cvt_pk_bf16_f32 v186, v191, v192
	v_cvt_pk_bf16_f32 v187, v193, v196
	v_cvt_pk_bf16_f32 v188, v197, v198
	v_cvt_pk_bf16_f32 v189, v199, v200
	ds_read_b64_tr_b16 v[192:193], v179 offset:62208
	ds_read_b64_tr_b16 v[190:191], v179 offset:59904
	ds_read_b64_tr_b16 v[194:195], v179 offset:59936
	ds_read_b64_tr_b16 v[198:199], v179 offset:59968
	ds_read_b64_tr_b16 v[202:203], v179 offset:60000
	ds_read_b64_tr_b16 v[196:197], v179 offset:62240
	ds_read_b64_tr_b16 v[200:201], v179 offset:62272
	ds_read_b64_tr_b16 v[204:205], v179 offset:62304
	s_waitcnt lgkmcnt(6)
	v_mfma_f32_16x16x32_bf16 v[52:55], v[186:189], v[190:193], v[52:55]
	s_waitcnt lgkmcnt(2)
	v_mfma_f32_16x16x32_bf16 v[56:59], v[186:189], v[194:197], v[56:59]
	s_waitcnt lgkmcnt(1)
	v_mfma_f32_16x16x32_bf16 v[60:63], v[186:189], v[198:201], v[60:63]
	s_waitcnt lgkmcnt(0)
	v_mfma_f32_16x16x32_bf16 v[48:51], v[186:189], v[202:205], v[48:51]
	v_cvt_pk_bf16_f32 v186, v207, v208
	v_cvt_pk_bf16_f32 v187, v64, v65
	v_cvt_pk_bf16_f32 v188, v209, v210
	v_cvt_pk_bf16_f32 v189, v211, v212
	ds_read_b64_tr_b16 v[192:193], v180 offset:11520
	ds_read_b64_tr_b16 v[190:191], v179 offset:64512
	ds_read_b64_tr_b16 v[194:195], v179 offset:64544
	ds_read_b64_tr_b16 v[198:199], v179 offset:64576
	ds_read_b64_tr_b16 v[202:203], v179 offset:64608
	ds_read_b64_tr_b16 v[196:197], v180 offset:11552
	ds_read_b64_tr_b16 v[200:201], v180 offset:11584
	ds_read_b64_tr_b16 v[204:205], v180 offset:11616
	s_waitcnt lgkmcnt(6)
	v_mfma_f32_16x16x32_bf16 v[52:55], v[186:189], v[190:193], v[52:55]
	s_waitcnt lgkmcnt(2)
	v_mfma_f32_16x16x32_bf16 v[56:59], v[186:189], v[194:197], v[56:59]
	s_waitcnt lgkmcnt(1)
	v_mfma_f32_16x16x32_bf16 v[60:63], v[186:189], v[198:201], v[60:63]
	s_waitcnt lgkmcnt(0)
	v_mfma_f32_16x16x32_bf16 v[48:51], v[186:189], v[202:205], v[48:51]
	v_cvt_pk_bf16_f32 v186, v213, v214
	v_cvt_pk_bf16_f32 v187, v215, v216
	v_cvt_pk_bf16_f32 v188, v217, v218
	v_cvt_pk_bf16_f32 v189, v219, v220
	ds_read_b64_tr_b16 v[192:193], v180 offset:16128
	ds_read_b64_tr_b16 v[190:191], v180 offset:13824
	ds_read_b64_tr_b16 v[194:195], v180 offset:13856
	ds_read_b64_tr_b16 v[198:199], v180 offset:13888
	ds_read_b64_tr_b16 v[202:203], v180 offset:13920
	ds_read_b64_tr_b16 v[196:197], v180 offset:16160
	ds_read_b64_tr_b16 v[200:201], v180 offset:16192
	ds_read_b64_tr_b16 v[204:205], v180 offset:16224
	s_waitcnt lgkmcnt(6)
	v_mfma_f32_16x16x32_bf16 v[52:55], v[186:189], v[190:193], v[52:55]
	s_waitcnt lgkmcnt(2)
	v_mfma_f32_16x16x32_bf16 v[56:59], v[186:189], v[194:197], v[56:59]
	s_waitcnt lgkmcnt(1)
	v_mfma_f32_16x16x32_bf16 v[60:63], v[186:189], v[198:201], v[60:63]
	s_waitcnt lgkmcnt(0)
	v_mfma_f32_16x16x32_bf16 v[48:51], v[186:189], v[202:205], v[48:51]
	v_cvt_pk_bf16_f32 v12, v221, v222
	v_cvt_pk_bf16_f32 v13, v13, v14
	v_mov_b32_e32 v14, v15
	ds_read_b64_tr_b16 v[186:187], v180 offset:18432
	ds_read_b64_tr_b16 v[190:191], v180 offset:18464
	ds_read_b64_tr_b16 v[194:195], v180 offset:18496
	ds_read_b64_tr_b16 v[198:199], v180 offset:18528
	v_mov_b32_e32 v188, v15
	v_mov_b32_e32 v189, v15
	v_mov_b32_e32 v192, v15
	v_mov_b32_e32 v193, v15
	v_mov_b32_e32 v196, v15
	v_mov_b32_e32 v197, v15
	v_mov_b32_e32 v200, v15
	v_mov_b32_e32 v201, v15
	s_waitcnt lgkmcnt(3)
	v_mfma_f32_16x16x32_bf16 v[52:55], v[12:15], v[186:189], v[52:55]
	s_waitcnt lgkmcnt(2)
	v_mfma_f32_16x16x32_bf16 v[56:59], v[12:15], v[190:193], v[56:59]
	s_waitcnt lgkmcnt(1)
	v_mfma_f32_16x16x32_bf16 v[60:63], v[12:15], v[194:197], v[60:63]
	s_waitcnt lgkmcnt(0)
; __device__ __forceinline__ bf16_t f2bf(float f) { return (bf16_t)cvtpk(f, 0.f); }
; __device__ void phase_attn(const Params& p, unsigned char* smem, int wave) {
;     ...
; #pragma unroll
;         for (int j = 0; j < 4; ++j) { const float dq = __shfl(den, 4 * gq + j); const float inv = __builtin_amdgcn_rcpf(dq);
;             const int tok = gbase + (i0 + 16 * w4 + 4 * gq + j) * d + res;
; #pragma unroll
;             for (int et = 0; et < 4; ++et) ato[(size_t)tok * 512 + h * 64 + 16 * et + ql] = f2bf(oacc[et][j] * inv); }
;         if (gq == 0) { const int tok = gbase + qi * d + res; lse[((size_t)br * NTOK + tok) * 8 + h] = mx * 0.6931471805599453f + __logf(den); }
	v_mfma_f32_16x16x32_bf16 v[48:51], v[12:15], v[198:201], v[48:51]
	v_or_b32_e32 v14, v206, v141
	v_add_f32_e32 v12, v47, v223
	v_lshlrev_b32_e32 v14, 2, v14
	ds_bpermute_b32 v47, v14, v12
	s_add_i32 s62, s62, s61
	s_lshl_b32 s18, s57, 7
	s_add_u32 s18, s59, s18
	v_or_b32_e32 v13, v139, v141
	s_addc_u32 s19, s60, 0
	v_mov_b32_e32 v139, v15
	s_waitcnt lgkmcnt(0)
	v_rcp_f32_e32 v47, v47
	v_lshl_add_u64 v[64:65], s[18:19], 0, v[138:139]
	v_lshlrev_b32_e32 v139, s58, v13
	v_add_u32_e32 v186, s62, v139
	v_ashrrev_i32_e32 v187, 31, v186
	v_lshlrev_b64 v[186:187], 10, v[186:187]
	v_mul_f32_e32 v52, v52, v47
	v_lshl_add_u64 v[186:187], v[64:65], 0, v[186:187]
	v_cvt_pk_bf16_f32 v52, v52, s0
	global_store_short v[186:187], v52, off
	v_mul_f32_e32 v52, v56, v47
	ds_bpermute_b32 v56, v14, v12 offset:4
	v_cvt_pk_bf16_f32 v52, v52, s0
	global_store_short v[186:187], v52, off offset:32
	v_mul_f32_e32 v52, v60, v47
	v_mul_f32_e32 v47, v48, v47
	v_cvt_pk_bf16_f32 v47, v47, s0
	global_store_short v[186:187], v47, off offset:96
	s_waitcnt lgkmcnt(0)
	v_rcp_f32_e32 v47, v56
	v_or_b32_e32 v48, 1, v13
	v_cvt_pk_bf16_f32 v52, v52, s0
	v_lshlrev_b32_e32 v48, s58, v48
	global_store_short v[186:187], v52, off offset:64
	v_add_u32_e32 v186, s62, v48
	v_ashrrev_i32_e32 v187, 31, v186
	v_lshlrev_b64 v[186:187], 10, v[186:187]
	v_mul_f32_e32 v48, v53, v47
	v_lshl_add_u64 v[186:187], v[64:65], 0, v[186:187]
	v_cvt_pk_bf16_f32 v48, v48, s0
	ds_bpermute_b32 v52, v14, v12 offset:8
	global_store_short v[186:187], v48, off
	v_mul_f32_e32 v48, v57, v47
	v_cvt_pk_bf16_f32 v48, v48, s0
	global_store_short v[186:187], v48, off offset:32
	v_mul_f32_e32 v48, v61, v47
	v_mul_f32_e32 v47, v49, v47
	v_cvt_pk_bf16_f32 v48, v48, s0
	v_cvt_pk_bf16_f32 v47, v47, s0
	global_store_short v[186:187], v48, off offset:64
	global_store_short v[186:187], v47, off offset:96
	s_waitcnt lgkmcnt(0)
	v_rcp_f32_e32 v47, v52
	v_or_b32_e32 v48, 2, v13
	v_lshlrev_b32_e32 v48, s58, v48
	v_add_u32_e32 v48, s62, v48
	v_or_b32_e32 v14, 12, v14
	v_ashrrev_i32_e32 v49, 31, v48
	ds_bpermute_b32 v14, v14, v12
	v_lshlrev_b64 v[48:49], 10, v[48:49]
	v_mul_f32_e32 v52, v54, v47
	v_lshl_add_u64 v[48:49], v[64:65], 0, v[48:49]
	v_cvt_pk_bf16_f32 v52, v52, s0
	global_store_short v[48:49], v52, off
	v_mul_f32_e32 v52, v58, v47
	v_cvt_pk_bf16_f32 v52, v52, s0
	global_store_short v[48:49], v52, off offset:32
	v_mul_f32_e32 v52, v62, v47
	v_mul_f32_e32 v47, v50, v47
	s_waitcnt lgkmcnt(0)
	v_rcp_f32_e32 v14, v14
	v_or_b32_e32 v13, 3, v13
	v_cvt_pk_bf16_f32 v52, v52, s0
	v_cvt_pk_bf16_f32 v47, v47, s0
	v_lshlrev_b32_e32 v13, s58, v13
	global_store_short v[48:49], v52, off offset:64
	global_store_short v[48:49], v47, off offset:96
	v_add_u32_e32 v48, s62, v13
	v_ashrrev_i32_e32 v49, 31, v48
	v_lshlrev_b64 v[48:49], 10, v[48:49]
	v_mul_f32_e32 v13, v55, v14
	v_lshl_add_u64 v[48:49], v[64:65], 0, v[48:49]
	v_cvt_pk_bf16_f32 v13, v13, s0
	global_store_short v[48:49], v13, off
	v_mul_f32_e32 v13, v59, v14
	v_cvt_pk_bf16_f32 v13, v13, s0
	global_store_short v[48:49], v13, off offset:32
	v_mul_f32_e32 v13, v63, v14
	v_cvt_pk_bf16_f32 v13, v13, s0
	global_store_short v[48:49], v13, off offset:64
	v_mul_f32_e32 v13, v51, v14
	v_cvt_pk_bf16_f32 v13, v13, s0
	global_store_short v[48:49], v13, off offset:96
	s_and_saveexec_b64 s[20:21], s[0:1]
	s_cbranch_execz .LBB0_719
	v_cmp_gt_f32_e32 vcc, s53, v12
	s_nop 1
	v_cndmask_b32_e64 v13, 0, 32, vcc
	v_ldexp_f32 v12, v12, v13
	v_log_f32_e32 v13, v12
	v_lshlrev_b32_e32 v12, s58, v45
	v_add_u32_e32 v12, s62, v12
	v_mul_f32_e32 v14, 0x3f317217, v13
	v_fma_f32 v14, v13, s54, -v14
	v_fmac_f32_e32 v14, 0x3377d1cf, v13
	v_fmac_f32_e32 v14, 0x3f317217, v13
	v_cmp_lt_f32_e64 s[18:19], |v13|, s55
	s_nop 1
	v_cndmask_b32_e64 v13, v13, v14, s[18:19]
	v_cndmask_b32_e32 v14, 0, v184, vcc
	v_sub_f32_e32 v14, v13, v14
	v_ashrrev_i32_e32 v13, 31, v12
	v_mad_i64_i32 v[12:13], s[18:19], s42, v185, v[12:13]
	v_lshlrev_b64 v[12:13], 5, v[12:13]
	v_lshl_add_u64 v[12:13], s[40:41], 0, v[12:13]
	s_lshl_b32 s42, s57, 2
	v_fmac_f32_e32 v14, 0x3f317218, v46
	v_lshl_add_u64 v[12:13], v[12:13], 0, s[42:43]
	global_store_dword v[12:13], v14, off
	s_branch .LBB0_719
